# P10 EpiRes<2>: residual prefetch (7 of 10 loads in first K-iteration), counted waits, mid-epilogue vmcnt(0) -> vmcnt(8)
# baseline (speedup 1.0000x reference)
.LBB0_1335:
	s_xor_b64 s[14:15], s[22:23], -1
	s_and_b64 s[22:23], s[22:23], exec
	s_cselect_b32 s24, s11, s17
	s_cselect_b32 s25, s10, s16
	s_cselect_b32 s26, s13, s19
	s_cselect_b32 s27, s12, s18
	s_add_u32 s16, s16, 0xb0080
	s_addc_u32 s17, s17, 0
	s_add_u32 s52, s18, 0x100
	s_addc_u32 s53, s19, 0
	s_mov_b32 s54, -2
	s_waitcnt vmcnt(0)
	ds_read_b128 v[128:131], v162
	ds_read_b128 v[132:135], v162 offset:1024
	ds_read_b128 v[146:149], v162 offset:2048
	ds_read_b128 v[150:153], v162 offset:3072
	s_add_u32 s18, s16, 0xfff50080
	s_addc_u32 s19, s17, -1
	s_cmp_eq_u32 s54, 40
	s_cselect_b32 s23, s24, s19
	s_cselect_b32 s22, s25, s18
	s_cselect_b32 s19, s26, s53
	s_cselect_b32 s18, s27, s52
	v_lshl_add_u64 v[158:159], s[16:17], 0, v[140:141]
	s_add_i32 m0, s35, 0xc000
	ds_read_b128 v[154:157], v163
	ds_read_b128 v[168:171], v163 offset:1024
	ds_read_b128 v[172:175], v163 offset:2048
	ds_read_b128 v[176:179], v163 offset:3072
	ds_read_b128 v[180:183], v163 offset:4096
	ds_read_b128 v[184:187], v163 offset:5120
	ds_read_b128 v[188:191], v163 offset:6144
	ds_read_b128 v[192:195], v163 offset:7168
	global_load_lds_dwordx4 v[158:159], off
	v_lshl_add_u64 v[158:159], s[16:17], 0, v[142:143]
	s_add_i32 m0, s35, 0xe000
	s_nop 0
	global_load_lds_dwordx4 v[158:159], off
	ds_read_b128 v[196:199], v164
	ds_read_b128 v[200:203], v164 offset:1024
	ds_read_b128 v[204:207], v164 offset:2048
	ds_read_b128 v[208:211], v164 offset:3072
	s_waitcnt lgkmcnt(0)
	s_waitcnt vmcnt(8)
	s_barrier
	s_setprio 1
	v_mfma_f32_16x16x32_bf16 v[124:127], v[128:131], v[154:157], 0
	v_mfma_f32_16x16x32_bf16 v[120:123], v[146:149], v[154:157], 0
	v_mfma_f32_16x16x32_bf16 v[116:119], v[128:131], v[172:175], 0
	v_mfma_f32_16x16x32_bf16 v[112:115], v[146:149], v[172:175], 0
	v_mfma_f32_16x16x32_bf16 v[92:95], v[128:131], v[180:183], 0
	v_mfma_f32_16x16x32_bf16 v[88:91], v[146:149], v[180:183], 0
	v_mfma_f32_16x16x32_bf16 v[76:79], v[128:131], v[188:191], 0
	v_mfma_f32_16x16x32_bf16 v[72:75], v[146:149], v[188:191], 0
	v_mfma_f32_16x16x32_bf16 v[124:127], v[132:135], v[168:171], v[124:127]
	v_mfma_f32_16x16x32_bf16 v[120:123], v[150:153], v[168:171], v[120:123]
	v_mfma_f32_16x16x32_bf16 v[116:119], v[132:135], v[176:179], v[116:119]
	v_mfma_f32_16x16x32_bf16 v[112:115], v[150:153], v[176:179], v[112:115]
	v_mfma_f32_16x16x32_bf16 v[92:95], v[132:135], v[184:187], v[92:95]
	v_mfma_f32_16x16x32_bf16 v[88:91], v[150:153], v[184:187], v[88:91]
	v_mfma_f32_16x16x32_bf16 v[76:79], v[132:135], v[192:195], v[76:79]
	v_mfma_f32_16x16x32_bf16 v[72:75], v[150:153], v[192:195], v[72:75]
	v_mfma_f32_16x16x32_bf16 v[108:111], v[196:199], v[154:157], 0
	v_mfma_f32_16x16x32_bf16 v[104:107], v[204:207], v[154:157], 0
	v_mfma_f32_16x16x32_bf16 v[100:103], v[196:199], v[172:175], 0
	v_mfma_f32_16x16x32_bf16 v[96:99], v[204:207], v[172:175], 0
	v_mfma_f32_16x16x32_bf16 v[84:87], v[196:199], v[180:183], 0
	v_mfma_f32_16x16x32_bf16 v[80:83], v[204:207], v[180:183], 0
	v_mfma_f32_16x16x32_bf16 v[68:71], v[196:199], v[188:191], 0
	v_mfma_f32_16x16x32_bf16 v[64:67], v[204:207], v[188:191], 0
	v_mfma_f32_16x16x32_bf16 v[108:111], v[200:203], v[168:171], v[108:111]
	v_mfma_f32_16x16x32_bf16 v[104:107], v[208:211], v[168:171], v[104:107]
	v_mfma_f32_16x16x32_bf16 v[100:103], v[200:203], v[176:179], v[100:103]
	v_mfma_f32_16x16x32_bf16 v[96:99], v[208:211], v[176:179], v[96:99]
	v_mfma_f32_16x16x32_bf16 v[84:87], v[200:203], v[184:187], v[84:87]
	v_mfma_f32_16x16x32_bf16 v[80:83], v[208:211], v[184:187], v[80:83]
	v_mfma_f32_16x16x32_bf16 v[68:71], v[200:203], v[192:195], v[68:71]
	v_mfma_f32_16x16x32_bf16 v[64:67], v[208:211], v[192:195], v[64:67]
	s_setprio 0
	s_barrier
	v_lshl_or_b32 v167, s51, 8, v161
	v_lshlrev_b32_e32 v167, 1, v167
	v_lshl_add_u32 v247, s50, 8, v160
	v_lshl_add_u32 v167, v247, 11, v167
	s_add_u32 s74, s6, 0x8000
	s_addc_u32 s75, s7, 0
	s_add_u32 s76, s6, 0x10000
	s_addc_u32 s77, s7, 0
	s_add_u32 s78, s6, 0x18000
	s_addc_u32 s79, s7, 0
	global_load_dwordx4 v[220:223], v167, s[6:7]
	global_load_dwordx4 v[224:227], v167, s[6:7] offset:64
	global_load_dwordx4 v[228:231], v167, s[74:75]
	global_load_dwordx4 v[232:235], v167, s[74:75] offset:64
	global_load_dwordx4 v[236:239], v167, s[76:77]
	global_load_dwordx4 v[240:243], v167, s[76:77] offset:64
	global_load_dwordx4 v[252:255], v167, s[78:79]
	ds_read_b128 v[154:157], v163 offset:16384
	ds_read_b128 v[168:171], v163 offset:17408
	ds_read_b128 v[172:175], v163 offset:18432
	ds_read_b128 v[176:179], v163 offset:19456
	ds_read_b128 v[180:183], v163 offset:20480
	ds_read_b128 v[184:187], v163 offset:21504
	ds_read_b128 v[188:191], v163 offset:22528
	ds_read_b128 v[192:195], v163 offset:23552
	s_mov_b32 m0, s33
	v_lshl_add_u64 v[158:159], s[18:19], 0, v[138:139]
	global_load_lds_dwordx4 v[158:159], off
	v_lshl_add_u64 v[212:213], s[18:19], 0, v[136:137]
	s_mov_b32 m0, s34
	s_nop 0
	global_load_lds_dwordx4 v[212:213], off
	s_mov_b32 m0, s35
	v_lshl_add_u64 v[214:215], s[22:23], 0, v[138:139]
	global_load_lds_dwordx4 v[214:215], off
	v_lshl_add_u64 v[216:217], s[22:23], 0, v[136:137]
	s_mov_b32 m0, s36
	s_nop 0
	global_load_lds_dwordx4 v[216:217], off
	s_add_u32 s56, s18, 0xb0000
	s_addc_u32 s57, s19, 0
	s_mov_b32 m0, s37
	v_lshl_add_u64 v[248:249], s[56:57], 0, v[138:139]
	global_load_lds_dwordx4 v[248:249], off
	v_lshl_add_u64 v[248:249], s[56:57], 0, v[136:137]
	s_mov_b32 m0, s38
	s_nop 0
	global_load_lds_dwordx4 v[248:249], off
	s_waitcnt lgkmcnt(0)
	s_waitcnt vmcnt(15)
	s_barrier
	s_setprio 1
	v_mfma_f32_16x16x32_bf16 v[60:63], v[128:131], v[154:157], 0
	v_mfma_f32_16x16x32_bf16 v[56:59], v[146:149], v[154:157], 0
	v_mfma_f32_16x16x32_bf16 v[44:47], v[128:131], v[172:175], 0
	v_mfma_f32_16x16x32_bf16 v[40:43], v[146:149], v[172:175], 0
	v_mfma_f32_16x16x32_bf16 v[28:31], v[128:131], v[180:183], 0
	v_mfma_f32_16x16x32_bf16 v[24:27], v[146:149], v[180:183], 0
	v_mfma_f32_16x16x32_bf16 v[12:15], v[128:131], v[188:191], 0
	v_mfma_f32_16x16x32_bf16 v[8:11], v[146:149], v[188:191], 0
	v_mfma_f32_16x16x32_bf16 v[60:63], v[132:135], v[168:171], v[60:63]
	v_mfma_f32_16x16x32_bf16 v[56:59], v[150:153], v[168:171], v[56:59]
	v_mfma_f32_16x16x32_bf16 v[44:47], v[132:135], v[176:179], v[44:47]
	v_mfma_f32_16x16x32_bf16 v[40:43], v[150:153], v[176:179], v[40:43]
	v_mfma_f32_16x16x32_bf16 v[28:31], v[132:135], v[184:187], v[28:31]
	v_mfma_f32_16x16x32_bf16 v[24:27], v[150:153], v[184:187], v[24:27]
	v_mfma_f32_16x16x32_bf16 v[12:15], v[132:135], v[192:195], v[12:15]
	v_mfma_f32_16x16x32_bf16 v[8:11], v[150:153], v[192:195], v[8:11]
	v_mfma_f32_16x16x32_bf16 v[52:55], v[196:199], v[154:157], 0
	v_mfma_f32_16x16x32_bf16 v[48:51], v[204:207], v[154:157], 0
	v_mfma_f32_16x16x32_bf16 v[36:39], v[196:199], v[172:175], 0
	v_mfma_f32_16x16x32_bf16 v[32:35], v[204:207], v[172:175], 0
	v_mfma_f32_16x16x32_bf16 v[20:23], v[196:199], v[180:183], 0
	v_mfma_f32_16x16x32_bf16 v[16:19], v[204:207], v[180:183], 0
	v_mfma_f32_16x16x32_bf16 v[4:7], v[196:199], v[188:191], 0
	v_mfma_f32_16x16x32_bf16 v[0:3], v[204:207], v[188:191], 0
	v_mfma_f32_16x16x32_bf16 v[52:55], v[200:203], v[168:171], v[52:55]
	v_mfma_f32_16x16x32_bf16 v[48:51], v[208:211], v[168:171], v[48:51]
	v_mfma_f32_16x16x32_bf16 v[36:39], v[200:203], v[176:179], v[36:39]
	v_mfma_f32_16x16x32_bf16 v[32:35], v[208:211], v[176:179], v[32:35]
	v_mfma_f32_16x16x32_bf16 v[20:23], v[200:203], v[184:187], v[20:23]
	v_mfma_f32_16x16x32_bf16 v[16:19], v[208:211], v[184:187], v[16:19]
	v_mfma_f32_16x16x32_bf16 v[4:7], v[200:203], v[192:195], v[4:7]
	v_mfma_f32_16x16x32_bf16 v[0:3], v[208:211], v[192:195], v[0:3]
	s_setprio 0
	s_barrier
	ds_read_b128 v[128:131], v165
	ds_read_b128 v[132:135], v165 offset:1024
	ds_read_b128 v[146:149], v165 offset:2048
	ds_read_b128 v[150:153], v165 offset:3072
	s_add_u32 s22, s22, 0xb0000
	s_addc_u32 s23, s23, 0
	s_mov_b32 m0, s39
	v_lshl_add_u64 v[196:197], s[22:23], 0, v[138:139]
	ds_read_b128 v[154:157], v163 offset:32768
	ds_read_b128 v[168:171], v163 offset:33792
	ds_read_b128 v[172:175], v163 offset:34816
	ds_read_b128 v[176:179], v163 offset:35840
	ds_read_b128 v[180:183], v163 offset:36864
	ds_read_b128 v[184:187], v163 offset:37888
	ds_read_b128 v[188:191], v163 offset:38912
	ds_read_b128 v[192:195], v163 offset:39936
	global_load_lds_dwordx4 v[196:197], off
	v_lshl_add_u64 v[196:197], s[22:23], 0, v[136:137]
	s_mov_b32 m0, s40
	s_nop 0
	global_load_lds_dwordx4 v[196:197], off
	ds_read_b128 v[196:199], v166
	ds_read_b128 v[200:203], v166 offset:1024
	ds_read_b128 v[204:207], v166 offset:2048
	ds_read_b128 v[208:211], v166 offset:3072
	s_waitcnt lgkmcnt(0)
	s_waitcnt vmcnt(15)
	s_barrier
	s_setprio 1
	v_mfma_f32_16x16x32_bf16 v[124:127], v[128:131], v[154:157], v[124:127]
	v_mfma_f32_16x16x32_bf16 v[120:123], v[146:149], v[154:157], v[120:123]
	v_mfma_f32_16x16x32_bf16 v[116:119], v[128:131], v[172:175], v[116:119]
	v_mfma_f32_16x16x32_bf16 v[112:115], v[146:149], v[172:175], v[112:115]
	v_mfma_f32_16x16x32_bf16 v[92:95], v[128:131], v[180:183], v[92:95]
	v_mfma_f32_16x16x32_bf16 v[88:91], v[146:149], v[180:183], v[88:91]
	v_mfma_f32_16x16x32_bf16 v[76:79], v[128:131], v[188:191], v[76:79]
	v_mfma_f32_16x16x32_bf16 v[72:75], v[146:149], v[188:191], v[72:75]
	v_mfma_f32_16x16x32_bf16 v[124:127], v[132:135], v[168:171], v[124:127]
	v_mfma_f32_16x16x32_bf16 v[120:123], v[150:153], v[168:171], v[120:123]
	v_mfma_f32_16x16x32_bf16 v[116:119], v[132:135], v[176:179], v[116:119]
	v_mfma_f32_16x16x32_bf16 v[112:115], v[150:153], v[176:179], v[112:115]
	v_mfma_f32_16x16x32_bf16 v[92:95], v[132:135], v[184:187], v[92:95]
	v_mfma_f32_16x16x32_bf16 v[88:91], v[150:153], v[184:187], v[88:91]
	v_mfma_f32_16x16x32_bf16 v[76:79], v[132:135], v[192:195], v[76:79]
	v_mfma_f32_16x16x32_bf16 v[72:75], v[150:153], v[192:195], v[72:75]
	v_mfma_f32_16x16x32_bf16 v[108:111], v[196:199], v[154:157], v[108:111]
	v_mfma_f32_16x16x32_bf16 v[104:107], v[204:207], v[154:157], v[104:107]
	v_mfma_f32_16x16x32_bf16 v[100:103], v[196:199], v[172:175], v[100:103]
	v_mfma_f32_16x16x32_bf16 v[96:99], v[204:207], v[172:175], v[96:99]
	v_mfma_f32_16x16x32_bf16 v[84:87], v[196:199], v[180:183], v[84:87]
	v_mfma_f32_16x16x32_bf16 v[80:83], v[204:207], v[180:183], v[80:83]
	v_mfma_f32_16x16x32_bf16 v[68:71], v[196:199], v[188:191], v[68:71]
	v_mfma_f32_16x16x32_bf16 v[64:67], v[204:207], v[188:191], v[64:67]
	v_mfma_f32_16x16x32_bf16 v[108:111], v[200:203], v[168:171], v[108:111]
	v_mfma_f32_16x16x32_bf16 v[104:107], v[208:211], v[168:171], v[104:107]
	v_mfma_f32_16x16x32_bf16 v[100:103], v[200:203], v[176:179], v[100:103]
	v_mfma_f32_16x16x32_bf16 v[96:99], v[208:211], v[176:179], v[96:99]
	v_mfma_f32_16x16x32_bf16 v[84:87], v[200:203], v[184:187], v[84:87]
	v_mfma_f32_16x16x32_bf16 v[80:83], v[208:211], v[184:187], v[80:83]
	v_mfma_f32_16x16x32_bf16 v[68:71], v[200:203], v[192:195], v[68:71]
	v_mfma_f32_16x16x32_bf16 v[64:67], v[208:211], v[192:195], v[64:67]
	s_setprio 0
	s_barrier
	ds_read_b128 v[154:157], v163 offset:49152
	ds_read_b128 v[168:171], v163 offset:50176
	ds_read_b128 v[172:175], v163 offset:51200
	ds_read_b128 v[176:179], v163 offset:52224
	ds_read_b128 v[180:183], v163 offset:53248
	ds_read_b128 v[184:187], v163 offset:54272
	ds_read_b128 v[188:191], v163 offset:55296
	ds_read_b128 v[192:195], v163 offset:56320
	s_mov_b32 m0, s41
	v_lshl_add_u64 v[158:159], v[158:159], 0, s[8:9]
	global_load_lds_dwordx4 v[158:159], off
	v_lshl_add_u64 v[158:159], v[212:213], 0, s[8:9]
	s_mov_b32 m0, s42
	s_nop 0
	global_load_lds_dwordx4 v[158:159], off
	s_mov_b32 m0, s43
	v_lshl_add_u64 v[158:159], v[214:215], 0, s[8:9]
	global_load_lds_dwordx4 v[158:159], off
	v_lshl_add_u64 v[158:159], v[216:217], 0, s[8:9]
	s_mov_b32 m0, s44
	s_nop 0
	global_load_lds_dwordx4 v[158:159], off
	s_add_u32 s18, s18, 0xb0080
	s_addc_u32 s19, s19, 0
	s_mov_b32 m0, s45
	v_lshl_add_u64 v[248:249], s[18:19], 0, v[138:139]
	global_load_lds_dwordx4 v[248:249], off
	v_lshl_add_u64 v[248:249], s[18:19], 0, v[136:137]
	s_mov_b32 m0, s46
	s_nop 0
	global_load_lds_dwordx4 v[248:249], off
	s_waitcnt lgkmcnt(0)
	s_waitcnt vmcnt(8)
	s_barrier
	s_setprio 1
	v_mfma_f32_16x16x32_bf16 v[60:63], v[128:131], v[154:157], v[60:63]
	v_mfma_f32_16x16x32_bf16 v[56:59], v[146:149], v[154:157], v[56:59]
	v_mfma_f32_16x16x32_bf16 v[44:47], v[128:131], v[172:175], v[44:47]
	v_mfma_f32_16x16x32_bf16 v[40:43], v[146:149], v[172:175], v[40:43]
	v_mfma_f32_16x16x32_bf16 v[28:31], v[128:131], v[180:183], v[28:31]
	v_mfma_f32_16x16x32_bf16 v[24:27], v[146:149], v[180:183], v[24:27]
	v_mfma_f32_16x16x32_bf16 v[12:15], v[128:131], v[188:191], v[12:15]
	v_mfma_f32_16x16x32_bf16 v[8:11], v[146:149], v[188:191], v[8:11]
	v_mfma_f32_16x16x32_bf16 v[60:63], v[132:135], v[168:171], v[60:63]
	v_mfma_f32_16x16x32_bf16 v[56:59], v[150:153], v[168:171], v[56:59]
	v_mfma_f32_16x16x32_bf16 v[44:47], v[132:135], v[176:179], v[44:47]
	v_mfma_f32_16x16x32_bf16 v[40:43], v[150:153], v[176:179], v[40:43]
	v_mfma_f32_16x16x32_bf16 v[28:31], v[132:135], v[184:187], v[28:31]
	v_mfma_f32_16x16x32_bf16 v[24:27], v[150:153], v[184:187], v[24:27]
	v_mfma_f32_16x16x32_bf16 v[12:15], v[132:135], v[192:195], v[12:15]
	v_mfma_f32_16x16x32_bf16 v[8:11], v[150:153], v[192:195], v[8:11]
	v_mfma_f32_16x16x32_bf16 v[52:55], v[196:199], v[154:157], v[52:55]
	v_mfma_f32_16x16x32_bf16 v[48:51], v[204:207], v[154:157], v[48:51]
	v_mfma_f32_16x16x32_bf16 v[36:39], v[196:199], v[172:175], v[36:39]
	v_mfma_f32_16x16x32_bf16 v[32:35], v[204:207], v[172:175], v[32:35]
	v_mfma_f32_16x16x32_bf16 v[20:23], v[196:199], v[180:183], v[20:23]
	v_mfma_f32_16x16x32_bf16 v[16:19], v[204:207], v[180:183], v[16:19]
	v_mfma_f32_16x16x32_bf16 v[4:7], v[196:199], v[188:191], v[4:7]
	v_mfma_f32_16x16x32_bf16 v[0:3], v[204:207], v[188:191], v[0:3]
	v_mfma_f32_16x16x32_bf16 v[52:55], v[200:203], v[168:171], v[52:55]
	v_mfma_f32_16x16x32_bf16 v[48:51], v[208:211], v[168:171], v[48:51]
	v_mfma_f32_16x16x32_bf16 v[36:39], v[200:203], v[176:179], v[36:39]
	v_mfma_f32_16x16x32_bf16 v[32:35], v[208:211], v[176:179], v[32:35]
	v_mfma_f32_16x16x32_bf16 v[20:23], v[200:203], v[184:187], v[20:23]
	v_mfma_f32_16x16x32_bf16 v[16:19], v[208:211], v[184:187], v[16:19]
	v_mfma_f32_16x16x32_bf16 v[4:7], v[200:203], v[192:195], v[4:7]
	v_mfma_f32_16x16x32_bf16 v[0:3], v[208:211], v[192:195], v[0:3]
	s_setprio 0
	s_add_i32 s54, s54, 2
	s_add_u32 s16, s16, 0x100
	s_addc_u32 s17, s17, 0
	s_add_u32 s52, s52, 0x100
	s_addc_u32 s53, s53, 0
	s_cmp_gt_u32 s54, 41
	s_barrier
.LBB0_1336:
	ds_read_b128 v[128:131], v162
	ds_read_b128 v[132:135], v162 offset:1024
	ds_read_b128 v[146:149], v162 offset:2048
	ds_read_b128 v[150:153], v162 offset:3072
	s_add_u32 s18, s16, 0xfff50080
	s_addc_u32 s19, s17, -1
	s_cmp_eq_u32 s54, 40
	s_cselect_b32 s23, s24, s19
	s_cselect_b32 s22, s25, s18
	s_cselect_b32 s19, s26, s53
	s_cselect_b32 s18, s27, s52
	v_lshl_add_u64 v[158:159], s[16:17], 0, v[140:141]
	s_add_i32 m0, s35, 0xc000
	ds_read_b128 v[154:157], v163
	ds_read_b128 v[168:171], v163 offset:1024
	ds_read_b128 v[172:175], v163 offset:2048
	ds_read_b128 v[176:179], v163 offset:3072
	ds_read_b128 v[180:183], v163 offset:4096
	ds_read_b128 v[184:187], v163 offset:5120
	ds_read_b128 v[188:191], v163 offset:6144
	ds_read_b128 v[192:195], v163 offset:7168
	global_load_lds_dwordx4 v[158:159], off
	v_lshl_add_u64 v[158:159], s[16:17], 0, v[142:143]
	s_add_i32 m0, s35, 0xe000
	s_nop 0
	global_load_lds_dwordx4 v[158:159], off
	ds_read_b128 v[196:199], v164
	ds_read_b128 v[200:203], v164 offset:1024
	ds_read_b128 v[204:207], v164 offset:2048
	ds_read_b128 v[208:211], v164 offset:3072
	s_waitcnt lgkmcnt(0)
	s_waitcnt vmcnt(8)
	s_barrier
	s_setprio 1
	v_mfma_f32_16x16x32_bf16 v[124:127], v[128:131], v[154:157], v[124:127]
	v_mfma_f32_16x16x32_bf16 v[120:123], v[146:149], v[154:157], v[120:123]
	v_mfma_f32_16x16x32_bf16 v[116:119], v[128:131], v[172:175], v[116:119]
	v_mfma_f32_16x16x32_bf16 v[112:115], v[146:149], v[172:175], v[112:115]
	v_mfma_f32_16x16x32_bf16 v[92:95], v[128:131], v[180:183], v[92:95]
	v_mfma_f32_16x16x32_bf16 v[88:91], v[146:149], v[180:183], v[88:91]
	v_mfma_f32_16x16x32_bf16 v[76:79], v[128:131], v[188:191], v[76:79]
	v_mfma_f32_16x16x32_bf16 v[72:75], v[146:149], v[188:191], v[72:75]
	v_mfma_f32_16x16x32_bf16 v[124:127], v[132:135], v[168:171], v[124:127]
	v_mfma_f32_16x16x32_bf16 v[120:123], v[150:153], v[168:171], v[120:123]
	v_mfma_f32_16x16x32_bf16 v[116:119], v[132:135], v[176:179], v[116:119]
	v_mfma_f32_16x16x32_bf16 v[112:115], v[150:153], v[176:179], v[112:115]
	v_mfma_f32_16x16x32_bf16 v[92:95], v[132:135], v[184:187], v[92:95]
	v_mfma_f32_16x16x32_bf16 v[88:91], v[150:153], v[184:187], v[88:91]
	v_mfma_f32_16x16x32_bf16 v[76:79], v[132:135], v[192:195], v[76:79]
	v_mfma_f32_16x16x32_bf16 v[72:75], v[150:153], v[192:195], v[72:75]
	v_mfma_f32_16x16x32_bf16 v[108:111], v[196:199], v[154:157], v[108:111]
	v_mfma_f32_16x16x32_bf16 v[104:107], v[204:207], v[154:157], v[104:107]
	v_mfma_f32_16x16x32_bf16 v[100:103], v[196:199], v[172:175], v[100:103]
	v_mfma_f32_16x16x32_bf16 v[96:99], v[204:207], v[172:175], v[96:99]
	v_mfma_f32_16x16x32_bf16 v[84:87], v[196:199], v[180:183], v[84:87]
	v_mfma_f32_16x16x32_bf16 v[80:83], v[204:207], v[180:183], v[80:83]
	v_mfma_f32_16x16x32_bf16 v[68:71], v[196:199], v[188:191], v[68:71]
	v_mfma_f32_16x16x32_bf16 v[64:67], v[204:207], v[188:191], v[64:67]
	v_mfma_f32_16x16x32_bf16 v[108:111], v[200:203], v[168:171], v[108:111]
	v_mfma_f32_16x16x32_bf16 v[104:107], v[208:211], v[168:171], v[104:107]
	v_mfma_f32_16x16x32_bf16 v[100:103], v[200:203], v[176:179], v[100:103]
	v_mfma_f32_16x16x32_bf16 v[96:99], v[208:211], v[176:179], v[96:99]
	v_mfma_f32_16x16x32_bf16 v[84:87], v[200:203], v[184:187], v[84:87]
	v_mfma_f32_16x16x32_bf16 v[80:83], v[208:211], v[184:187], v[80:83]
	v_mfma_f32_16x16x32_bf16 v[68:71], v[200:203], v[192:195], v[68:71]
	v_mfma_f32_16x16x32_bf16 v[64:67], v[208:211], v[192:195], v[64:67]
	s_setprio 0
	s_barrier
	ds_read_b128 v[154:157], v163 offset:16384
	ds_read_b128 v[168:171], v163 offset:17408
	ds_read_b128 v[172:175], v163 offset:18432
	ds_read_b128 v[176:179], v163 offset:19456
	ds_read_b128 v[180:183], v163 offset:20480
	ds_read_b128 v[184:187], v163 offset:21504
	ds_read_b128 v[188:191], v163 offset:22528
	ds_read_b128 v[192:195], v163 offset:23552
	s_mov_b32 m0, s33
	v_lshl_add_u64 v[158:159], s[18:19], 0, v[138:139]
	global_load_lds_dwordx4 v[158:159], off
	v_lshl_add_u64 v[212:213], s[18:19], 0, v[136:137]
	s_mov_b32 m0, s34
	s_nop 0
	global_load_lds_dwordx4 v[212:213], off
	s_mov_b32 m0, s35
	v_lshl_add_u64 v[214:215], s[22:23], 0, v[138:139]
	global_load_lds_dwordx4 v[214:215], off
	v_lshl_add_u64 v[216:217], s[22:23], 0, v[136:137]
	s_mov_b32 m0, s36
	s_nop 0
	global_load_lds_dwordx4 v[216:217], off
	s_add_u32 s56, s18, 0xb0000
	s_addc_u32 s57, s19, 0
	s_mov_b32 m0, s37
	v_lshl_add_u64 v[248:249], s[56:57], 0, v[138:139]
	global_load_lds_dwordx4 v[248:249], off
	v_lshl_add_u64 v[248:249], s[56:57], 0, v[136:137]
	s_mov_b32 m0, s38
	s_nop 0
	global_load_lds_dwordx4 v[248:249], off
	s_waitcnt lgkmcnt(0)
	s_waitcnt vmcnt(8)
	s_barrier
	s_setprio 1
	v_mfma_f32_16x16x32_bf16 v[60:63], v[128:131], v[154:157], v[60:63]
	v_mfma_f32_16x16x32_bf16 v[56:59], v[146:149], v[154:157], v[56:59]
	v_mfma_f32_16x16x32_bf16 v[44:47], v[128:131], v[172:175], v[44:47]
	v_mfma_f32_16x16x32_bf16 v[40:43], v[146:149], v[172:175], v[40:43]
	v_mfma_f32_16x16x32_bf16 v[28:31], v[128:131], v[180:183], v[28:31]
	v_mfma_f32_16x16x32_bf16 v[24:27], v[146:149], v[180:183], v[24:27]
	v_mfma_f32_16x16x32_bf16 v[12:15], v[128:131], v[188:191], v[12:15]
	v_mfma_f32_16x16x32_bf16 v[8:11], v[146:149], v[188:191], v[8:11]
	v_mfma_f32_16x16x32_bf16 v[60:63], v[132:135], v[168:171], v[60:63]
	v_mfma_f32_16x16x32_bf16 v[56:59], v[150:153], v[168:171], v[56:59]
	v_mfma_f32_16x16x32_bf16 v[44:47], v[132:135], v[176:179], v[44:47]
	v_mfma_f32_16x16x32_bf16 v[40:43], v[150:153], v[176:179], v[40:43]
	v_mfma_f32_16x16x32_bf16 v[28:31], v[132:135], v[184:187], v[28:31]
	v_mfma_f32_16x16x32_bf16 v[24:27], v[150:153], v[184:187], v[24:27]
	v_mfma_f32_16x16x32_bf16 v[12:15], v[132:135], v[192:195], v[12:15]
	v_mfma_f32_16x16x32_bf16 v[8:11], v[150:153], v[192:195], v[8:11]
	v_mfma_f32_16x16x32_bf16 v[52:55], v[196:199], v[154:157], v[52:55]
	v_mfma_f32_16x16x32_bf16 v[48:51], v[204:207], v[154:157], v[48:51]
	v_mfma_f32_16x16x32_bf16 v[36:39], v[196:199], v[172:175], v[36:39]
	v_mfma_f32_16x16x32_bf16 v[32:35], v[204:207], v[172:175], v[32:35]
	v_mfma_f32_16x16x32_bf16 v[20:23], v[196:199], v[180:183], v[20:23]
	v_mfma_f32_16x16x32_bf16 v[16:19], v[204:207], v[180:183], v[16:19]
	v_mfma_f32_16x16x32_bf16 v[4:7], v[196:199], v[188:191], v[4:7]
	v_mfma_f32_16x16x32_bf16 v[0:3], v[204:207], v[188:191], v[0:3]
	v_mfma_f32_16x16x32_bf16 v[52:55], v[200:203], v[168:171], v[52:55]
	v_mfma_f32_16x16x32_bf16 v[48:51], v[208:211], v[168:171], v[48:51]
	v_mfma_f32_16x16x32_bf16 v[36:39], v[200:203], v[176:179], v[36:39]
	v_mfma_f32_16x16x32_bf16 v[32:35], v[208:211], v[176:179], v[32:35]
	v_mfma_f32_16x16x32_bf16 v[20:23], v[200:203], v[184:187], v[20:23]
	v_mfma_f32_16x16x32_bf16 v[16:19], v[208:211], v[184:187], v[16:19]
	v_mfma_f32_16x16x32_bf16 v[4:7], v[200:203], v[192:195], v[4:7]
	v_mfma_f32_16x16x32_bf16 v[0:3], v[208:211], v[192:195], v[0:3]
	s_setprio 0
	s_barrier
	ds_read_b128 v[128:131], v165
	ds_read_b128 v[132:135], v165 offset:1024
	ds_read_b128 v[146:149], v165 offset:2048
	ds_read_b128 v[150:153], v165 offset:3072
	s_add_u32 s22, s22, 0xb0000
	s_addc_u32 s23, s23, 0
	s_mov_b32 m0, s39
	v_lshl_add_u64 v[196:197], s[22:23], 0, v[138:139]
	ds_read_b128 v[154:157], v163 offset:32768
	ds_read_b128 v[168:171], v163 offset:33792
	ds_read_b128 v[172:175], v163 offset:34816
	ds_read_b128 v[176:179], v163 offset:35840
	ds_read_b128 v[180:183], v163 offset:36864
	ds_read_b128 v[184:187], v163 offset:37888
	ds_read_b128 v[188:191], v163 offset:38912
	ds_read_b128 v[192:195], v163 offset:39936
	global_load_lds_dwordx4 v[196:197], off
	v_lshl_add_u64 v[196:197], s[22:23], 0, v[136:137]
	s_mov_b32 m0, s40
	s_nop 0
	global_load_lds_dwordx4 v[196:197], off
	ds_read_b128 v[196:199], v166
	ds_read_b128 v[200:203], v166 offset:1024
	ds_read_b128 v[204:207], v166 offset:2048
	ds_read_b128 v[208:211], v166 offset:3072
	s_waitcnt lgkmcnt(0)
	s_waitcnt vmcnt(8)
	s_barrier
	s_setprio 1
	v_mfma_f32_16x16x32_bf16 v[124:127], v[128:131], v[154:157], v[124:127]
	v_mfma_f32_16x16x32_bf16 v[120:123], v[146:149], v[154:157], v[120:123]
	v_mfma_f32_16x16x32_bf16 v[116:119], v[128:131], v[172:175], v[116:119]
	v_mfma_f32_16x16x32_bf16 v[112:115], v[146:149], v[172:175], v[112:115]
	v_mfma_f32_16x16x32_bf16 v[92:95], v[128:131], v[180:183], v[92:95]
	v_mfma_f32_16x16x32_bf16 v[88:91], v[146:149], v[180:183], v[88:91]
	v_mfma_f32_16x16x32_bf16 v[76:79], v[128:131], v[188:191], v[76:79]
	v_mfma_f32_16x16x32_bf16 v[72:75], v[146:149], v[188:191], v[72:75]
	v_mfma_f32_16x16x32_bf16 v[124:127], v[132:135], v[168:171], v[124:127]
	v_mfma_f32_16x16x32_bf16 v[120:123], v[150:153], v[168:171], v[120:123]
	v_mfma_f32_16x16x32_bf16 v[116:119], v[132:135], v[176:179], v[116:119]
	v_mfma_f32_16x16x32_bf16 v[112:115], v[150:153], v[176:179], v[112:115]
	v_mfma_f32_16x16x32_bf16 v[92:95], v[132:135], v[184:187], v[92:95]
	v_mfma_f32_16x16x32_bf16 v[88:91], v[150:153], v[184:187], v[88:91]
	v_mfma_f32_16x16x32_bf16 v[76:79], v[132:135], v[192:195], v[76:79]
	v_mfma_f32_16x16x32_bf16 v[72:75], v[150:153], v[192:195], v[72:75]
	v_mfma_f32_16x16x32_bf16 v[108:111], v[196:199], v[154:157], v[108:111]
	v_mfma_f32_16x16x32_bf16 v[104:107], v[204:207], v[154:157], v[104:107]
	v_mfma_f32_16x16x32_bf16 v[100:103], v[196:199], v[172:175], v[100:103]
	v_mfma_f32_16x16x32_bf16 v[96:99], v[204:207], v[172:175], v[96:99]
	v_mfma_f32_16x16x32_bf16 v[84:87], v[196:199], v[180:183], v[84:87]
	v_mfma_f32_16x16x32_bf16 v[80:83], v[204:207], v[180:183], v[80:83]
	v_mfma_f32_16x16x32_bf16 v[68:71], v[196:199], v[188:191], v[68:71]
	v_mfma_f32_16x16x32_bf16 v[64:67], v[204:207], v[188:191], v[64:67]
	v_mfma_f32_16x16x32_bf16 v[108:111], v[200:203], v[168:171], v[108:111]
	v_mfma_f32_16x16x32_bf16 v[104:107], v[208:211], v[168:171], v[104:107]
	v_mfma_f32_16x16x32_bf16 v[100:103], v[200:203], v[176:179], v[100:103]
	v_mfma_f32_16x16x32_bf16 v[96:99], v[208:211], v[176:179], v[96:99]
	v_mfma_f32_16x16x32_bf16 v[84:87], v[200:203], v[184:187], v[84:87]
	v_mfma_f32_16x16x32_bf16 v[80:83], v[208:211], v[184:187], v[80:83]
	v_mfma_f32_16x16x32_bf16 v[68:71], v[200:203], v[192:195], v[68:71]
	v_mfma_f32_16x16x32_bf16 v[64:67], v[208:211], v[192:195], v[64:67]
	s_setprio 0
	s_barrier
	ds_read_b128 v[154:157], v163 offset:49152
	ds_read_b128 v[168:171], v163 offset:50176
	ds_read_b128 v[172:175], v163 offset:51200
	ds_read_b128 v[176:179], v163 offset:52224
	ds_read_b128 v[180:183], v163 offset:53248
	ds_read_b128 v[184:187], v163 offset:54272
	ds_read_b128 v[188:191], v163 offset:55296
	ds_read_b128 v[192:195], v163 offset:56320
	s_mov_b32 m0, s41
	v_lshl_add_u64 v[158:159], v[158:159], 0, s[8:9]
	global_load_lds_dwordx4 v[158:159], off
	v_lshl_add_u64 v[158:159], v[212:213], 0, s[8:9]
	s_mov_b32 m0, s42
	s_nop 0
	global_load_lds_dwordx4 v[158:159], off
	s_mov_b32 m0, s43
	v_lshl_add_u64 v[158:159], v[214:215], 0, s[8:9]
	global_load_lds_dwordx4 v[158:159], off
	v_lshl_add_u64 v[158:159], v[216:217], 0, s[8:9]
	s_mov_b32 m0, s44
	s_nop 0
	global_load_lds_dwordx4 v[158:159], off
	s_add_u32 s18, s18, 0xb0080
	s_addc_u32 s19, s19, 0
	s_mov_b32 m0, s45
	v_lshl_add_u64 v[248:249], s[18:19], 0, v[138:139]
	global_load_lds_dwordx4 v[248:249], off
	v_lshl_add_u64 v[248:249], s[18:19], 0, v[136:137]
	s_mov_b32 m0, s46
	s_nop 0
	global_load_lds_dwordx4 v[248:249], off
	s_waitcnt lgkmcnt(0)
	s_waitcnt vmcnt(8)
	s_barrier
	s_setprio 1
	v_mfma_f32_16x16x32_bf16 v[60:63], v[128:131], v[154:157], v[60:63]
	v_mfma_f32_16x16x32_bf16 v[56:59], v[146:149], v[154:157], v[56:59]
	v_mfma_f32_16x16x32_bf16 v[44:47], v[128:131], v[172:175], v[44:47]
	v_mfma_f32_16x16x32_bf16 v[40:43], v[146:149], v[172:175], v[40:43]
	v_mfma_f32_16x16x32_bf16 v[28:31], v[128:131], v[180:183], v[28:31]
	v_mfma_f32_16x16x32_bf16 v[24:27], v[146:149], v[180:183], v[24:27]
	v_mfma_f32_16x16x32_bf16 v[12:15], v[128:131], v[188:191], v[12:15]
	v_mfma_f32_16x16x32_bf16 v[8:11], v[146:149], v[188:191], v[8:11]
	v_mfma_f32_16x16x32_bf16 v[60:63], v[132:135], v[168:171], v[60:63]
	v_mfma_f32_16x16x32_bf16 v[56:59], v[150:153], v[168:171], v[56:59]
	v_mfma_f32_16x16x32_bf16 v[44:47], v[132:135], v[176:179], v[44:47]
	v_mfma_f32_16x16x32_bf16 v[40:43], v[150:153], v[176:179], v[40:43]
	v_mfma_f32_16x16x32_bf16 v[28:31], v[132:135], v[184:187], v[28:31]
	v_mfma_f32_16x16x32_bf16 v[24:27], v[150:153], v[184:187], v[24:27]
	v_mfma_f32_16x16x32_bf16 v[12:15], v[132:135], v[192:195], v[12:15]
	v_mfma_f32_16x16x32_bf16 v[8:11], v[150:153], v[192:195], v[8:11]
	v_mfma_f32_16x16x32_bf16 v[52:55], v[196:199], v[154:157], v[52:55]
	v_mfma_f32_16x16x32_bf16 v[48:51], v[204:207], v[154:157], v[48:51]
	v_mfma_f32_16x16x32_bf16 v[36:39], v[196:199], v[172:175], v[36:39]
	v_mfma_f32_16x16x32_bf16 v[32:35], v[204:207], v[172:175], v[32:35]
	v_mfma_f32_16x16x32_bf16 v[20:23], v[196:199], v[180:183], v[20:23]
	v_mfma_f32_16x16x32_bf16 v[16:19], v[204:207], v[180:183], v[16:19]
	v_mfma_f32_16x16x32_bf16 v[4:7], v[196:199], v[188:191], v[4:7]
	v_mfma_f32_16x16x32_bf16 v[0:3], v[204:207], v[188:191], v[0:3]
	v_mfma_f32_16x16x32_bf16 v[52:55], v[200:203], v[168:171], v[52:55]
	v_mfma_f32_16x16x32_bf16 v[48:51], v[208:211], v[168:171], v[48:51]
	v_mfma_f32_16x16x32_bf16 v[36:39], v[200:203], v[176:179], v[36:39]
	v_mfma_f32_16x16x32_bf16 v[32:35], v[208:211], v[176:179], v[32:35]
	v_mfma_f32_16x16x32_bf16 v[20:23], v[200:203], v[184:187], v[20:23]
	v_mfma_f32_16x16x32_bf16 v[16:19], v[208:211], v[184:187], v[16:19]
	v_mfma_f32_16x16x32_bf16 v[4:7], v[200:203], v[192:195], v[4:7]
	v_mfma_f32_16x16x32_bf16 v[0:3], v[208:211], v[192:195], v[0:3]
	s_setprio 0
	s_add_i32 s54, s54, 2
	s_add_u32 s16, s16, 0x100
	s_addc_u32 s17, s17, 0
	s_add_u32 s52, s52, 0x100
	s_addc_u32 s53, s53, 0
	s_cmp_gt_u32 s54, 41
	s_barrier
	s_cbranch_scc0 .LBB0_1336
	v_lshl_or_b32 v128, s51, 8, v161
	v_lshl_add_u32 v156, s50, 8, v160
	v_ashrrev_i32_e32 v129, 31, v128
	v_lshlrev_b64 v[154:155], 1, v[128:129]
	v_ashrrev_i32_e32 v157, 31, v156
	v_lshl_add_u64 v[130:131], s[6:7], 0, v[154:155]
	v_lshlrev_b64 v[132:133], 11, v[156:157]
	v_or_b32_e32 v200, 16, v156
	v_lshl_add_u64 v[132:133], v[130:131], 0, v[132:133]
	v_ashrrev_i32_e32 v201, 31, v200
	v_mov_b32_e32 v168, v220
	v_mov_b32_e32 v169, v221
	v_mov_b32_e32 v170, v222
	v_mov_b32_e32 v171, v223
	v_mov_b32_e32 v172, v224
	v_mov_b32_e32 v173, v225
	v_mov_b32_e32 v174, v226
	v_mov_b32_e32 v175, v227
	v_lshlrev_b64 v[132:133], 11, v[200:201]
	v_lshl_add_u64 v[132:133], v[130:131], 0, v[132:133]
	v_mov_b32_e32 v176, v228
	v_mov_b32_e32 v177, v229
	v_mov_b32_e32 v178, v230
	v_mov_b32_e32 v179, v231
	v_mov_b32_e32 v180, v232
	v_mov_b32_e32 v181, v233
	v_mov_b32_e32 v182, v234
	v_mov_b32_e32 v183, v235
	v_or_b32_e32 v158, 32, v156
	v_ashrrev_i32_e32 v159, 31, v158
	v_lshlrev_b64 v[146:147], 2, v[128:129]
	v_lshlrev_b64 v[128:129], 11, v[158:159]
	v_lshl_add_u64 v[128:129], v[130:131], 0, v[128:129]
	v_mov_b32_e32 v184, v236
	v_mov_b32_e32 v185, v237
	v_mov_b32_e32 v186, v238
	v_mov_b32_e32 v187, v239
	v_or_b32_e32 v152, 48, v156
	v_add_u32_e32 v148, 0x80, v156
	v_add_u32_e32 v150, 0x90, v156
	v_readlane_b32 s16, v246, 62
	v_ashrrev_i32_e32 v153, 31, v152
	v_ashrrev_i32_e32 v149, 31, v148
	v_lshlrev_b64 v[132:133], 12, v[156:157]
	v_ashrrev_i32_e32 v151, 31, v150
	v_readlane_b32 s17, v246, 63
	v_lshlrev_b64 v[134:135], 11, v[152:153]
	v_lshlrev_b64 v[188:189], 11, v[148:149]
	v_lshl_add_u64 v[132:133], s[16:17], 0, v[132:133]
	v_lshlrev_b64 v[190:191], 11, v[150:151]
	v_lshl_add_u64 v[130:131], v[130:131], 0, v[134:135]
	v_lshl_add_u64 v[134:135], s[6:7], 0, v[188:189]
	v_lshl_add_u64 v[202:203], v[132:133], 0, v[146:147]
	v_lshl_add_u64 v[132:133], s[6:7], 0, v[190:191]
	v_mov_b32_e32 v188, v240
	v_mov_b32_e32 v189, v241
	v_mov_b32_e32 v190, v242
	v_mov_b32_e32 v191, v243
	v_mov_b32_e32 v192, v252
	v_mov_b32_e32 v193, v253
	v_mov_b32_e32 v194, v254
	v_mov_b32_e32 v195, v255
	global_load_dwordx4 v[196:199], v[130:131], off offset:64
	v_lshl_add_u64 v[128:129], v[134:135], 0, v[154:155]
	v_lshl_add_u64 v[204:205], v[132:133], 0, v[154:155]
	global_load_dwordx4 v[132:135], v[128:129], off
	s_nop 0
	global_load_dwordx4 v[128:131], v[128:129], off offset:64
	v_readlane_b32 s18, v245, 0
	v_readlane_b32 s19, v245, 1
	s_and_b64 vcc, exec, s[14:15]
	s_mov_b32 s51, s48
	s_mov_b32 s50, s49
	s_mov_b64 s[18:19], s[12:13]
	v_lshlrev_b32_e32 v206, 16, v168
	v_and_b32_e32 v207, 0xffff0000, v168
	v_lshlrev_b32_e32 v168, 16, v169
	v_and_b32_e32 v169, 0xffff0000, v169
	v_lshlrev_b32_e32 v208, 16, v170
	v_and_b32_e32 v209, 0xffff0000, v170
	v_lshlrev_b32_e32 v170, 16, v171
	v_and_b32_e32 v171, 0xffff0000, v171
	v_lshlrev_b32_e32 v210, 16, v172
	v_and_b32_e32 v211, 0xffff0000, v172
	v_lshlrev_b32_e32 v172, 16, v173
	v_and_b32_e32 v173, 0xffff0000, v173
	v_lshlrev_b32_e32 v212, 16, v174
	v_and_b32_e32 v213, 0xffff0000, v174
	v_lshlrev_b32_e32 v174, 16, v175
	v_and_b32_e32 v175, 0xffff0000, v175
	v_pk_add_f32 v[126:127], v[126:127], v[168:169]
	v_pk_add_f32 v[124:125], v[124:125], v[206:207]
	v_pk_add_f32 v[120:121], v[120:121], v[208:209]
	v_pk_add_f32 v[122:123], v[122:123], v[170:171]
	v_pk_add_f32 v[110:111], v[110:111], v[172:173]
	v_pk_add_f32 v[108:109], v[108:109], v[210:211]
	v_pk_add_f32 v[106:107], v[106:107], v[174:175]
	v_pk_add_f32 v[104:105], v[104:105], v[212:213]
	global_store_dwordx4 v[202:203], v[124:127], off nt
	global_store_dwordx4 v[202:203], v[120:123], off offset:16 nt
	global_store_dwordx4 v[202:203], v[108:111], off offset:128 nt
	global_store_dwordx4 v[202:203], v[104:107], off offset:144 nt
	v_lshlrev_b32_e32 v120, 16, v182
	v_and_b32_e32 v121, 0xffff0000, v182
	v_pk_add_f32 v[96:97], v[96:97], v[120:121]
	v_lshlrev_b64 v[120:121], 12, v[200:201]
	v_lshlrev_b32_e32 v214, 16, v176
	v_and_b32_e32 v215, 0xffff0000, v176
	v_lshlrev_b32_e32 v176, 16, v177
	v_and_b32_e32 v177, 0xffff0000, v177
	v_lshlrev_b32_e32 v216, 16, v178
	v_and_b32_e32 v217, 0xffff0000, v178
	v_lshlrev_b32_e32 v178, 16, v179
	v_and_b32_e32 v179, 0xffff0000, v179
	global_load_dwordx4 v[108:111], v[204:205], off
	global_load_dwordx4 v[104:107], v[204:205], off offset:64
	v_lshl_add_u64 v[120:121], s[16:17], 0, v[120:121]
	v_lshlrev_b32_e32 v218, 16, v180
	v_and_b32_e32 v219, 0xffff0000, v180
	v_lshlrev_b32_e32 v180, 16, v181
	v_pk_add_f32 v[118:119], v[118:119], v[176:177]
	v_pk_add_f32 v[116:117], v[116:117], v[214:215]
	v_pk_add_f32 v[114:115], v[114:115], v[178:179]
	v_pk_add_f32 v[112:113], v[112:113], v[216:217]
	v_and_b32_e32 v181, 0xffff0000, v181
	v_lshlrev_b32_e32 v122, 16, v183
	v_and_b32_e32 v123, 0xffff0000, v183
	v_lshl_add_u64 v[120:121], v[120:121], 0, v[146:147]
	v_pk_add_f32 v[102:103], v[102:103], v[180:181]
	v_pk_add_f32 v[100:101], v[100:101], v[218:219]
	v_pk_add_f32 v[98:99], v[98:99], v[122:123]
	global_store_dwordx4 v[120:121], v[116:119], off nt
	global_store_dwordx4 v[120:121], v[112:115], off offset:16 nt
	global_store_dwordx4 v[120:121], v[100:103], off offset:128 nt
	global_store_dwordx4 v[120:121], v[96:99], off offset:144 nt
	v_add_u32_e32 v112, 0xa0, v156
	v_lshlrev_b32_e32 v114, 16, v184
	v_and_b32_e32 v115, 0xffff0000, v184
	v_ashrrev_i32_e32 v113, 31, v112
	v_pk_add_f32 v[92:93], v[92:93], v[114:115]
	v_lshlrev_b32_e32 v114, 16, v186
	v_and_b32_e32 v115, 0xffff0000, v186
	v_lshlrev_b64 v[96:97], 11, v[112:113]
	v_pk_add_f32 v[88:89], v[88:89], v[114:115]
	v_lshlrev_b32_e32 v114, 16, v188
	v_and_b32_e32 v115, 0xffff0000, v188
	v_lshl_add_u64 v[96:97], s[6:7], 0, v[96:97]
	v_lshlrev_b32_e32 v116, 16, v185
	v_and_b32_e32 v117, 0xffff0000, v185
	v_pk_add_f32 v[84:85], v[84:85], v[114:115]
	v_lshlrev_b32_e32 v114, 16, v190
	v_and_b32_e32 v115, 0xffff0000, v190
	v_lshl_add_u64 v[96:97], v[96:97], 0, v[154:155]
	v_pk_add_f32 v[94:95], v[94:95], v[116:117]
	v_lshlrev_b32_e32 v116, 16, v187
	v_and_b32_e32 v117, 0xffff0000, v187
	v_pk_add_f32 v[80:81], v[80:81], v[114:115]
	v_lshlrev_b64 v[114:115], 12, v[158:159]
	global_load_dwordx4 v[100:103], v[96:97], off
	s_nop 0
	global_load_dwordx4 v[96:99], v[96:97], off offset:64
	v_pk_add_f32 v[90:91], v[90:91], v[116:117]
	v_lshlrev_b32_e32 v116, 16, v189
	v_and_b32_e32 v117, 0xffff0000, v189
	v_lshl_add_u64 v[114:115], s[16:17], 0, v[114:115]
	v_pk_add_f32 v[86:87], v[86:87], v[116:117]
	v_lshlrev_b32_e32 v116, 16, v191
	v_and_b32_e32 v117, 0xffff0000, v191
	v_lshl_add_u64 v[114:115], v[114:115], 0, v[146:147]
	v_pk_add_f32 v[82:83], v[82:83], v[116:117]
	global_store_dwordx4 v[114:115], v[92:95], off nt
	global_store_dwordx4 v[114:115], v[88:91], off offset:16 nt
	global_store_dwordx4 v[114:115], v[84:87], off offset:128 nt
	global_store_dwordx4 v[114:115], v[80:83], off offset:144 nt
	v_add_u32_e32 v88, 0xb0, v156
	v_ashrrev_i32_e32 v89, 31, v88
	v_lshlrev_b64 v[80:81], 11, v[88:89]
	v_lshl_add_u64 v[80:81], s[6:7], 0, v[80:81]
	v_lshl_add_u64 v[80:81], v[80:81], 0, v[154:155]
	global_load_dwordx4 v[84:87], v[80:81], off
	s_nop 0
	global_load_dwordx4 v[80:83], v[80:81], off offset:64
	v_lshlrev_b32_e32 v90, 16, v192
	v_and_b32_e32 v91, 0xffff0000, v192
	v_pk_add_f32 v[76:77], v[76:77], v[90:91]
	v_lshlrev_b32_e32 v90, 16, v194
	v_and_b32_e32 v91, 0xffff0000, v194
	v_pk_add_f32 v[72:73], v[72:73], v[90:91]
	s_waitcnt vmcnt(19)
	v_lshlrev_b32_e32 v90, 16, v196
	v_and_b32_e32 v91, 0xffff0000, v196
	v_lshlrev_b32_e32 v92, 16, v193
	v_and_b32_e32 v93, 0xffff0000, v193
	v_pk_add_f32 v[68:69], v[68:69], v[90:91]
	v_lshlrev_b32_e32 v90, 16, v198
	v_and_b32_e32 v91, 0xffff0000, v198
	v_pk_add_f32 v[78:79], v[78:79], v[92:93]
	v_lshlrev_b32_e32 v92, 16, v195
	v_and_b32_e32 v93, 0xffff0000, v195
	v_pk_add_f32 v[64:65], v[64:65], v[90:91]
	v_lshlrev_b64 v[90:91], 12, v[152:153]
	v_pk_add_f32 v[74:75], v[74:75], v[92:93]
	v_lshlrev_b32_e32 v92, 16, v197
	v_and_b32_e32 v93, 0xffff0000, v197
	v_lshl_add_u64 v[90:91], s[16:17], 0, v[90:91]
	v_pk_add_f32 v[70:71], v[70:71], v[92:93]
	v_lshlrev_b32_e32 v92, 16, v199
	v_and_b32_e32 v93, 0xffff0000, v199
	v_lshl_add_u64 v[90:91], v[90:91], 0, v[146:147]
	v_pk_add_f32 v[66:67], v[66:67], v[92:93]
	global_store_dwordx4 v[90:91], v[76:79], off nt
	global_store_dwordx4 v[90:91], v[72:75], off offset:16 nt
	global_store_dwordx4 v[90:91], v[68:71], off offset:128 nt
	global_store_dwordx4 v[90:91], v[64:67], off offset:144 nt
	s_nop 1
	s_waitcnt vmcnt(21)
	v_lshlrev_b32_e32 v64, 16, v132
	v_and_b32_e32 v65, 0xffff0000, v132
	v_pk_add_f32 v[60:61], v[60:61], v[64:65]
	v_lshlrev_b32_e32 v64, 16, v134
	v_and_b32_e32 v65, 0xffff0000, v134
	v_pk_add_f32 v[56:57], v[56:57], v[64:65]
	v_lshlrev_b32_e32 v64, 16, v128
	v_and_b32_e32 v65, 0xffff0000, v128
	v_lshlrev_b32_e32 v66, 16, v133
	v_and_b32_e32 v67, 0xffff0000, v133
	v_pk_add_f32 v[52:53], v[52:53], v[64:65]
	v_lshlrev_b32_e32 v64, 16, v130
	v_and_b32_e32 v65, 0xffff0000, v130
	v_pk_add_f32 v[62:63], v[62:63], v[66:67]
	v_lshlrev_b32_e32 v66, 16, v135
	v_and_b32_e32 v67, 0xffff0000, v135
	v_pk_add_f32 v[48:49], v[48:49], v[64:65]
	v_lshlrev_b64 v[64:65], 12, v[148:149]
	v_pk_add_f32 v[58:59], v[58:59], v[66:67]
	v_lshlrev_b32_e32 v66, 16, v129
	v_and_b32_e32 v67, 0xffff0000, v129
	v_lshl_add_u64 v[64:65], s[16:17], 0, v[64:65]
	v_pk_add_f32 v[54:55], v[54:55], v[66:67]
	v_lshlrev_b32_e32 v66, 16, v131
	v_and_b32_e32 v67, 0xffff0000, v131
	v_lshl_add_u64 v[64:65], v[64:65], 0, v[146:147]
	v_pk_add_f32 v[50:51], v[50:51], v[66:67]
	global_store_dwordx4 v[64:65], v[60:63], off nt
	global_store_dwordx4 v[64:65], v[56:59], off offset:16 nt
	global_store_dwordx4 v[64:65], v[52:55], off offset:128 nt
	global_store_dwordx4 v[64:65], v[48:51], off offset:144 nt
	s_waitcnt vmcnt(8)
	s_nop 0
	v_lshlrev_b32_e32 v48, 16, v108
	v_and_b32_e32 v49, 0xffff0000, v108
	v_pk_add_f32 v[44:45], v[44:45], v[48:49]
	v_lshlrev_b32_e32 v48, 16, v110
	v_and_b32_e32 v49, 0xffff0000, v110
	v_pk_add_f32 v[40:41], v[40:41], v[48:49]
	v_lshlrev_b32_e32 v48, 16, v104
	v_and_b32_e32 v49, 0xffff0000, v104
	v_lshlrev_b32_e32 v50, 16, v109
	v_and_b32_e32 v51, 0xffff0000, v109
	v_pk_add_f32 v[36:37], v[36:37], v[48:49]
	v_lshlrev_b32_e32 v48, 16, v106
	v_and_b32_e32 v49, 0xffff0000, v106
	v_pk_add_f32 v[46:47], v[46:47], v[50:51]
	v_lshlrev_b32_e32 v50, 16, v111
	v_and_b32_e32 v51, 0xffff0000, v111
	v_pk_add_f32 v[32:33], v[32:33], v[48:49]
	v_lshlrev_b64 v[48:49], 12, v[150:151]
	v_pk_add_f32 v[42:43], v[42:43], v[50:51]
	v_lshlrev_b32_e32 v50, 16, v105
	v_and_b32_e32 v51, 0xffff0000, v105
	v_lshl_add_u64 v[48:49], s[16:17], 0, v[48:49]
	v_pk_add_f32 v[38:39], v[38:39], v[50:51]
	v_lshlrev_b32_e32 v50, 16, v107
	v_and_b32_e32 v51, 0xffff0000, v107
	v_lshl_add_u64 v[48:49], v[48:49], 0, v[146:147]
	v_pk_add_f32 v[34:35], v[34:35], v[50:51]
	global_store_dwordx4 v[48:49], v[44:47], off nt
	global_store_dwordx4 v[48:49], v[40:43], off offset:16 nt
	global_store_dwordx4 v[48:49], v[36:39], off offset:128 nt
	global_store_dwordx4 v[48:49], v[32:35], off offset:144 nt
	s_nop 1
	v_lshlrev_b32_e32 v32, 16, v100
	v_and_b32_e32 v33, 0xffff0000, v100
	v_pk_add_f32 v[28:29], v[28:29], v[32:33]
	v_lshlrev_b32_e32 v32, 16, v102
	v_and_b32_e32 v33, 0xffff0000, v102
	v_pk_add_f32 v[24:25], v[24:25], v[32:33]
	v_lshlrev_b32_e32 v32, 16, v96
	v_and_b32_e32 v33, 0xffff0000, v96
	v_lshlrev_b32_e32 v34, 16, v101
	v_and_b32_e32 v35, 0xffff0000, v101
	v_pk_add_f32 v[20:21], v[20:21], v[32:33]
	v_lshlrev_b32_e32 v32, 16, v98
	v_and_b32_e32 v33, 0xffff0000, v98
	v_pk_add_f32 v[30:31], v[30:31], v[34:35]
	v_lshlrev_b32_e32 v34, 16, v103
	v_and_b32_e32 v35, 0xffff0000, v103
	v_pk_add_f32 v[16:17], v[16:17], v[32:33]
	v_lshlrev_b64 v[32:33], 12, v[112:113]
	v_pk_add_f32 v[26:27], v[26:27], v[34:35]
	v_lshlrev_b32_e32 v34, 16, v97
	v_and_b32_e32 v35, 0xffff0000, v97
	v_lshl_add_u64 v[32:33], s[16:17], 0, v[32:33]
	v_pk_add_f32 v[22:23], v[22:23], v[34:35]
	v_lshlrev_b32_e32 v34, 16, v99
	v_and_b32_e32 v35, 0xffff0000, v99
	v_lshl_add_u64 v[32:33], v[32:33], 0, v[146:147]
	v_pk_add_f32 v[18:19], v[18:19], v[34:35]
	global_store_dwordx4 v[32:33], v[28:31], off nt
	global_store_dwordx4 v[32:33], v[24:27], off offset:16 nt
	global_store_dwordx4 v[32:33], v[20:23], off offset:128 nt
	global_store_dwordx4 v[32:33], v[16:19], off offset:144 nt
	s_nop 1
	v_lshlrev_b32_e32 v16, 16, v84
	v_and_b32_e32 v17, 0xffff0000, v84
	v_pk_add_f32 v[12:13], v[12:13], v[16:17]
	v_lshlrev_b32_e32 v16, 16, v86
	v_and_b32_e32 v17, 0xffff0000, v86
	v_pk_add_f32 v[8:9], v[8:9], v[16:17]
	v_lshlrev_b32_e32 v16, 16, v80
	v_and_b32_e32 v17, 0xffff0000, v80
	v_lshlrev_b32_e32 v18, 16, v85
	v_and_b32_e32 v19, 0xffff0000, v85
	v_pk_add_f32 v[4:5], v[4:5], v[16:17]
	v_lshlrev_b32_e32 v16, 16, v82
	v_and_b32_e32 v17, 0xffff0000, v82
	v_pk_add_f32 v[14:15], v[14:15], v[18:19]
	v_lshlrev_b32_e32 v18, 16, v87
	v_and_b32_e32 v19, 0xffff0000, v87
	v_pk_add_f32 v[0:1], v[0:1], v[16:17]
	v_lshlrev_b64 v[16:17], 12, v[88:89]
	v_pk_add_f32 v[10:11], v[10:11], v[18:19]
	v_lshlrev_b32_e32 v18, 16, v81
	v_and_b32_e32 v19, 0xffff0000, v81
	v_lshl_add_u64 v[16:17], s[16:17], 0, v[16:17]
	v_pk_add_f32 v[6:7], v[6:7], v[18:19]
	v_lshlrev_b32_e32 v18, 16, v83
	v_and_b32_e32 v19, 0xffff0000, v83
	v_lshl_add_u64 v[16:17], v[16:17], 0, v[146:147]
	s_mov_b64 s[16:17], s[10:11]
	v_pk_add_f32 v[2:3], v[2:3], v[18:19]
	global_store_dwordx4 v[16:17], v[12:15], off nt
	global_store_dwordx4 v[16:17], v[8:11], off offset:16 nt
	global_store_dwordx4 v[16:17], v[4:7], off offset:128 nt
	global_store_dwordx4 v[16:17], v[0:3], off offset:144 nt
	s_cbranch_vccz .LBB0_1331
	s_branch .LBB0_1340
